# attention item loop: back-edge copy of the loop top with store-aware vmcnt (the shared waits also drained the previous item's output stores)
# speedup vs baseline: 1.0022x; 1.0022x over previous
.LBB0_406:
	s_or_b64 exec, exec, s[2:3]
	s_mov_b64 s[2:3], 0
	s_and_b64 vcc, exec, s[14:15]
	s_mov_b32 s16, s31
	s_cbranch_vccnz .LBB0_419
	s_sub_i32 s17, s16, s0
	s_lshl_b32 s12, s17, 7
	s_and_b32 s12, s12, 0x80
	v_add_u32_e32 v40, s12, v112
	v_mad_u64_u32 v[40:41], s[14:15], v40, s18, v[118:119]
	s_barrier
	s_waitcnt vmcnt(9)
	ds_write_b128 v140, v[12:15]
	s_waitcnt vmcnt(7)
	ds_write_b128 v40, v[24:27] offset:18432
	s_waitcnt vmcnt(6)
	ds_write_b128 v40, v[28:31] offset:55296
	ds_write_b128 v141, v[20:23]
	v_add_u32_e32 v40, s12, v113
	v_mad_u64_u32 v[40:41], s[14:15], v40, s18, v[118:119]
	s_waitcnt vmcnt(5)
	ds_write_b128 v40, v[32:35] offset:18432
	s_waitcnt vmcnt(4)
	ds_write_b128 v40, v[36:39] offset:55296
	s_branch .LBB0_409
